# gate/up epilogue scheduled depth-first by row-group (first exp at slot 15, software-pipelined groups) instead of breadth-first across the rstd chains
# baseline (speedup 1.0000x reference)
; __device__ __forceinline__ unsigned pk2(float lo, float hi) { unsigned r; asm("v_cvt_pk_bf16_f32 %0, %1, %2" : "=v"(r) : "v"(lo), "v"(hi)); return r; }
; __device__ __forceinline__ float sigmoidf_(float v) { return __builtin_amdgcn_rcpf(1.0f + fexp(-v)); }
; __device__ __forceinline__ void row_rstd8(const ssq_t* ss, int row0, float (&r)[8]) {
;     ssq_t sv[8];
; #pragma unroll
;     for (int k = 0; k < 8; ++k) sv[k] = ss[row0 + (k >> 2) * 128 + (k & 3) * 16];
;     asm volatile("" ::: "memory");
; #pragma unroll
;     for (int k = 0; k < 8; ++k) r[k] = rsqrtf((float)sv[k] * (1.0f / SSQ_SCALE) * (1.0f / D) + EPS);
; }
;     __device__ __forceinline__ bool operator()(f32x4 (&acc)[2][2][4][2], const pg8::Unit& u, int wr, int wc, int fr, int fq) const {
;         const int row0 = u.pm * 256 + wr * 64 + fr, col0 = u.pn * 128 + wc * 32 + 8 * fq;
;         float rr[8]; row_rstd8(ss, row0, rr);
; #pragma unroll
;         for (int ai = 0; ai < 2; ++ai)
; #pragma unroll
;             for (int m = 0; m < 4; ++m) {
;                 const int row = row0 + ai * 128 + m * 16; const float r = rr[ai * 4 + m];
;                 float o[8];
; #pragma unroll
;                 for (int n = 0; n < 2; ++n)
; #pragma unroll
;                     for (int j = 0; j < 4; ++j) { const float gv = acc[ai][0][m][n][j] * r, uv = acc[ai][1][m][n][j] * r; o[n * 4 + j] = gv * sigmoidf_(gv) * uv; }
;                 u32x4 w; w.x = pk2(o[0], o[1]); w.y = pk2(o[2], o[3]); w.z = pk2(o[4], o[5]); w.w = pk2(o[6], o[7]);
;                 *(u32x4*)(act + (size_t)row * FF + col0) = w;
.LBB0_97:
	v_lshl_add_u32 v140, s35, 8, v151
	v_readlane_b32 s6, v255, 31
	v_ashrrev_i32_e32 v141, 31, v140
	v_readlane_b32 s7, v255, 32
	v_lshl_or_b32 v156, s34, 7, v155
	v_ashrrev_i32_e32 v157, 31, v156
	v_lshl_add_u64 v[142:143], v[140:141], 3, s[6:7]
	global_load_dwordx2 v[160:161], v[142:143], off
	global_load_dwordx2 v[162:163], v[142:143], off offset:128
	global_load_dwordx2 v[164:165], v[142:143], off offset:256
	global_load_dwordx2 v[166:167], v[142:143], off offset:384
	global_load_dwordx2 v[146:147], v[142:143], off offset:1024
	global_load_dwordx2 v[148:149], v[142:143], off offset:1152
	global_load_dwordx2 v[144:145], v[142:143], off offset:1280
	s_nop 0
	global_load_dwordx2 v[142:143], v[142:143], off offset:1408
	v_lshlrev_b64 v[156:157], 1, v[156:157]
	v_lshl_add_u64 v[156:157], v[156:157], 0, s[90:91]
	v_mad_i64_i32 v[156:157], s[6:7], v140, s37, v[156:157]
	v_mov_b32_e32 v140, 1.0
	v_mov_b32_e32 v141, 1.0
	v_pk_mul_f32 v[122:123], v[122:123], v[126:127]
	v_pk_mul_f32 v[124:125], v[124:125], v[128:129]
	v_pk_mul_f32 v[114:115], v[114:115], v[118:119]
	v_pk_mul_f32 v[116:117], v[116:117], v[120:121]
	v_pk_mul_f32 v[106:107], v[106:107], v[110:111]
	v_pk_mul_f32 v[108:109], v[108:109], v[112:113]
	v_pk_mul_f32 v[98:99], v[98:99], v[102:103]
	v_pk_mul_f32 v[100:101], v[100:101], v[104:105]
	v_pk_mul_f32 v[90:91], v[90:91], v[94:95]
	v_pk_mul_f32 v[92:93], v[92:93], v[96:97]
	v_pk_mul_f32 v[82:83], v[82:83], v[86:87]
	v_pk_mul_f32 v[84:85], v[84:85], v[88:89]
	v_pk_mul_f32 v[74:75], v[74:75], v[78:79]
	v_pk_mul_f32 v[76:77], v[76:77], v[80:81]
	v_pk_mul_f32 v[66:67], v[66:67], v[70:71]
	v_pk_mul_f32 v[68:69], v[68:69], v[72:73]
	v_pk_mul_f32 v[58:59], v[58:59], v[62:63]
	v_pk_mul_f32 v[60:61], v[60:61], v[64:65]
	v_pk_mul_f32 v[50:51], v[50:51], v[54:55]
	v_pk_mul_f32 v[52:53], v[52:53], v[56:57]
	v_pk_mul_f32 v[42:43], v[42:43], v[46:47]
	v_pk_mul_f32 v[44:45], v[44:45], v[48:49]
	v_pk_mul_f32 v[34:35], v[34:35], v[38:39]
	v_pk_mul_f32 v[36:37], v[36:37], v[40:41]
	v_pk_mul_f32 v[26:27], v[26:27], v[30:31]
	v_pk_mul_f32 v[28:29], v[28:29], v[32:33]
	v_pk_mul_f32 v[18:19], v[18:19], v[22:23]
	v_pk_mul_f32 v[20:21], v[20:21], v[24:25]
	v_pk_mul_f32 v[10:11], v[10:11], v[14:15]
	v_pk_mul_f32 v[12:13], v[12:13], v[16:17]
	v_pk_mul_f32 v[2:3], v[2:3], v[6:7]
	v_pk_mul_f32 v[4:5], v[4:5], v[8:9]
	s_mov_b32 s6, 0x2c000
	s_mov_b32 s7, 0
	s_waitcnt vmcnt(0)
	v_ffbh_u32_e32 v168, v161
	v_min_u32_e32 v168, 32, v168
	v_lshlrev_b64 v[160:161], v168, v[160:161]
	v_min_u32_e32 v198, 1, v160
	v_or_b32_e32 v198, v161, v198
	v_cvt_f32_u32_e32 v198, v198
	v_sub_u32_e32 v168, 32, v168
	v_ldexp_f32 v198, v198, v168
	v_mul_f32_e32 v198, 0x33800000, v198
	v_fmamk_f32 v198, v198, 0x3a000000, v218
	v_rsq_f32_e32 v160, v198
	v_ffbh_u32_e32 v170, v163
	v_mul_f32_e32 v168, 0xbfb8aa3b, v160
	v_pk_mul_f32 v[126:127], v[126:127], v[168:169] op_sel_hi:[1,0]
	v_pk_mul_f32 v[128:129], v[128:129], v[168:169] op_sel_hi:[1,0]
	v_exp_f32_e32 v126, v126
	v_pk_mul_f32 v[118:119], v[118:119], v[168:169] op_sel_hi:[1,0]
	v_pk_mul_f32 v[120:121], v[120:121], v[168:169] op_sel_hi:[1,0]
	v_exp_f32_e32 v127, v127
	v_mul_f32_e32 v198, v160, v160
	v_pk_add_f32 v[126:127], v[126:127], v[140:141]
	v_exp_f32_e32 v128, v128
	v_pk_mul_f32 v[122:123], v[122:123], v[198:199] op_sel_hi:[1,0]
	v_pk_mul_f32 v[124:125], v[124:125], v[198:199] op_sel_hi:[1,0]
	v_exp_f32_e32 v129, v129
	v_pk_mul_f32 v[114:115], v[114:115], v[198:199] op_sel_hi:[1,0]
	v_pk_add_f32 v[128:129], v[128:129], v[140:141]
	v_exp_f32_e32 v118, v118
	v_pk_mul_f32 v[116:117], v[116:117], v[198:199] op_sel_hi:[1,0]
	v_min_u32_e32 v170, 32, v170
	v_exp_f32_e32 v119, v119
	v_lshlrev_b64 v[162:163], v170, v[162:163]
	v_pk_add_f32 v[118:119], v[118:119], v[140:141]
	v_exp_f32_e32 v120, v120
	v_min_u32_e32 v200, 1, v162
	v_or_b32_e32 v200, v163, v200
	v_exp_f32_e32 v121, v121
	v_cvt_f32_u32_e32 v200, v200
	v_pk_add_f32 v[120:121], v[120:121], v[140:141]
	v_rcp_f32_e32 v126, v126
	v_sub_u32_e32 v170, 32, v170
	v_ldexp_f32 v200, v200, v170
	v_rcp_f32_e32 v127, v127
	v_mul_f32_e32 v200, 0x33800000, v200
	v_pk_mul_f32 v[122:123], v[122:123], v[126:127]
	v_rcp_f32_e32 v128, v128
	v_cvt_pk_bf16_f32 v126, v122, v123
	v_fmamk_f32 v200, v200, 0x3a000000, v218
	v_rcp_f32_e32 v129, v129
	v_ffbh_u32_e32 v172, v165
	v_pk_mul_f32 v[124:125], v[124:125], v[128:129]
	v_rcp_f32_e32 v118, v118
	v_cvt_pk_bf16_f32 v127, v124, v125
	v_min_u32_e32 v172, 32, v172
	v_rcp_f32_e32 v119, v119
	v_lshlrev_b64 v[164:165], v172, v[164:165]
	v_pk_mul_f32 v[114:115], v[114:115], v[118:119]
	v_rcp_f32_e32 v120, v120
	v_cvt_pk_bf16_f32 v128, v114, v115
	v_min_u32_e32 v202, 1, v164
	v_rcp_f32_e32 v121, v121
	v_or_b32_e32 v202, v165, v202
	v_pk_mul_f32 v[116:117], v[116:117], v[120:121]
	v_rsq_f32_e32 v162, v200
	v_cvt_pk_bf16_f32 v129, v116, v117
	global_store_dwordx4 v[156:157], v[126:129], off
	v_mul_f32_e32 v170, 0xbfb8aa3b, v162
	v_pk_mul_f32 v[110:111], v[110:111], v[170:171] op_sel_hi:[1,0]
	v_pk_mul_f32 v[112:113], v[112:113], v[170:171] op_sel_hi:[1,0]
	v_exp_f32_e32 v110, v110
	v_pk_mul_f32 v[102:103], v[102:103], v[170:171] op_sel_hi:[1,0]
	v_pk_mul_f32 v[104:105], v[104:105], v[170:171] op_sel_hi:[1,0]
	v_exp_f32_e32 v111, v111
	v_mul_f32_e32 v200, v162, v162
	v_pk_add_f32 v[110:111], v[110:111], v[140:141]
	v_exp_f32_e32 v112, v112
	v_pk_mul_f32 v[106:107], v[106:107], v[200:201] op_sel_hi:[1,0]
	v_pk_mul_f32 v[108:109], v[108:109], v[200:201] op_sel_hi:[1,0]
	v_exp_f32_e32 v113, v113
	v_pk_mul_f32 v[98:99], v[98:99], v[200:201] op_sel_hi:[1,0]
	v_pk_add_f32 v[112:113], v[112:113], v[140:141]
	v_exp_f32_e32 v102, v102
; __device__ __forceinline__ unsigned pk2(float lo, float hi) { unsigned r; asm("v_cvt_pk_bf16_f32 %0, %1, %2" : "=v"(r) : "v"(lo), "v"(hi)); return r; }
; __device__ __forceinline__ float sigmoidf_(float v) { return __builtin_amdgcn_rcpf(1.0f + fexp(-v)); }
;     __device__ __forceinline__ bool operator()(f32x4 (&acc)[2][2][4][2], const pg8::Unit& u, int wr, int wc, int fr, int fq) const {
;     ...
;                 const int row = row0 + ai * 128 + m * 16; const float r = rr[ai * 4 + m];
;                 float o[8];
; #pragma unroll
;                 for (int n = 0; n < 2; ++n)
; #pragma unroll
;                     for (int j = 0; j < 4; ++j) { const float gv = acc[ai][0][m][n][j] * r, uv = acc[ai][1][m][n][j] * r; o[n * 4 + j] = gv * sigmoidf_(gv) * uv; }
;                 u32x4 w; w.x = pk2(o[0], o[1]); w.y = pk2(o[2], o[3]); w.z = pk2(o[4], o[5]); w.w = pk2(o[6], o[7]);
;                 *(u32x4*)(act + (size_t)row * FF + col0) = w;
	v_pk_mul_f32 v[100:101], v[100:101], v[200:201] op_sel_hi:[1,0]
	v_lshl_add_u64 v[156:157], v[156:157], 0, s[6:7]
	v_exp_f32_e32 v103, v103
	v_cvt_f32_u32_e32 v202, v202
	v_pk_add_f32 v[102:103], v[102:103], v[140:141]
	v_exp_f32_e32 v104, v104
	v_sub_u32_e32 v172, 32, v172
	v_ldexp_f32 v202, v202, v172
	v_exp_f32_e32 v105, v105
	v_mul_f32_e32 v202, 0x33800000, v202
	v_pk_add_f32 v[104:105], v[104:105], v[140:141]
	v_rcp_f32_e32 v110, v110
	v_fmamk_f32 v202, v202, 0x3a000000, v218
	v_ffbh_u32_e32 v174, v167
	v_rcp_f32_e32 v111, v111
	v_min_u32_e32 v174, 32, v174
	v_pk_mul_f32 v[106:107], v[106:107], v[110:111]
	v_rcp_f32_e32 v112, v112
	v_cvt_pk_bf16_f32 v110, v106, v107
	v_lshlrev_b64 v[166:167], v174, v[166:167]
	v_rcp_f32_e32 v113, v113
	v_min_u32_e32 v204, 1, v166
	v_pk_mul_f32 v[108:109], v[108:109], v[112:113]
	v_rcp_f32_e32 v102, v102
	v_cvt_pk_bf16_f32 v111, v108, v109
	v_or_b32_e32 v204, v167, v204
	v_rcp_f32_e32 v103, v103
	v_cvt_f32_u32_e32 v204, v204
	v_pk_mul_f32 v[98:99], v[98:99], v[102:103]
	v_rcp_f32_e32 v104, v104
	v_cvt_pk_bf16_f32 v112, v98, v99
	v_sub_u32_e32 v174, 32, v174
	v_rcp_f32_e32 v105, v105
	v_ldexp_f32 v204, v204, v174
	v_pk_mul_f32 v[100:101], v[100:101], v[104:105]
	v_rsq_f32_e32 v164, v202
	v_cvt_pk_bf16_f32 v113, v100, v101
	global_store_dwordx4 v[156:157], v[110:113], off
	v_mul_f32_e32 v172, 0xbfb8aa3b, v164
	v_pk_mul_f32 v[94:95], v[94:95], v[172:173] op_sel_hi:[1,0]
	v_pk_mul_f32 v[96:97], v[96:97], v[172:173] op_sel_hi:[1,0]
	v_exp_f32_e32 v94, v94
	v_pk_mul_f32 v[86:87], v[86:87], v[172:173] op_sel_hi:[1,0]
	v_pk_mul_f32 v[88:89], v[88:89], v[172:173] op_sel_hi:[1,0]
	v_exp_f32_e32 v95, v95
	v_mul_f32_e32 v202, v164, v164
	v_pk_add_f32 v[94:95], v[94:95], v[140:141]
	v_exp_f32_e32 v96, v96
	v_pk_mul_f32 v[90:91], v[90:91], v[202:203] op_sel_hi:[1,0]
	v_pk_mul_f32 v[92:93], v[92:93], v[202:203] op_sel_hi:[1,0]
	v_exp_f32_e32 v97, v97
	v_pk_mul_f32 v[82:83], v[82:83], v[202:203] op_sel_hi:[1,0]
	v_pk_add_f32 v[96:97], v[96:97], v[140:141]
	v_exp_f32_e32 v86, v86
	v_pk_mul_f32 v[84:85], v[84:85], v[202:203] op_sel_hi:[1,0]
	v_lshl_add_u64 v[156:157], v[156:157], 0, s[6:7]
	v_exp_f32_e32 v87, v87
	v_mul_f32_e32 v204, 0x33800000, v204
	v_pk_add_f32 v[86:87], v[86:87], v[140:141]
	v_exp_f32_e32 v88, v88
	v_fmamk_f32 v204, v204, 0x3a000000, v218
	v_ffbh_u32_e32 v176, v147
	v_exp_f32_e32 v89, v89
	v_min_u32_e32 v176, 32, v176
	v_pk_add_f32 v[88:89], v[88:89], v[140:141]
	v_rcp_f32_e32 v94, v94
	v_lshlrev_b64 v[146:147], v176, v[146:147]
	v_min_u32_e32 v206, 1, v146
	v_rcp_f32_e32 v95, v95
	v_or_b32_e32 v206, v147, v206
	v_pk_mul_f32 v[90:91], v[90:91], v[94:95]
	v_rcp_f32_e32 v96, v96
	v_cvt_pk_bf16_f32 v94, v90, v91
	v_cvt_f32_u32_e32 v206, v206
	v_rcp_f32_e32 v97, v97
	v_sub_u32_e32 v176, 32, v176
	v_pk_mul_f32 v[92:93], v[92:93], v[96:97]
	v_rcp_f32_e32 v86, v86
	v_cvt_pk_bf16_f32 v95, v92, v93
	v_ldexp_f32 v206, v206, v176
	v_rcp_f32_e32 v87, v87
	v_mul_f32_e32 v206, 0x33800000, v206
	v_pk_mul_f32 v[82:83], v[82:83], v[86:87]
	v_rcp_f32_e32 v88, v88
	v_cvt_pk_bf16_f32 v96, v82, v83
	v_fmamk_f32 v206, v206, 0x3a000000, v218
	v_rcp_f32_e32 v89, v89
	v_ffbh_u32_e32 v178, v149
	v_pk_mul_f32 v[84:85], v[84:85], v[88:89]
	v_rsq_f32_e32 v166, v204
	v_cvt_pk_bf16_f32 v97, v84, v85
	global_store_dwordx4 v[156:157], v[94:97], off
	v_rsq_f32_e32 v146, v206
	v_mul_f32_e32 v174, 0xbfb8aa3b, v166
	v_pk_mul_f32 v[78:79], v[78:79], v[174:175] op_sel_hi:[1,0]
	v_pk_mul_f32 v[80:81], v[80:81], v[174:175] op_sel_hi:[1,0]
	v_exp_f32_e32 v78, v78
	v_pk_mul_f32 v[70:71], v[70:71], v[174:175] op_sel_hi:[1,0]
	v_pk_mul_f32 v[72:73], v[72:73], v[174:175] op_sel_hi:[1,0]
	v_exp_f32_e32 v79, v79
	v_mul_f32_e32 v204, v166, v166
	v_pk_add_f32 v[78:79], v[78:79], v[140:141]
	v_exp_f32_e32 v80, v80
	v_pk_mul_f32 v[74:75], v[74:75], v[204:205] op_sel_hi:[1,0]
	v_pk_mul_f32 v[76:77], v[76:77], v[204:205] op_sel_hi:[1,0]
	v_exp_f32_e32 v81, v81
	v_pk_mul_f32 v[66:67], v[66:67], v[204:205] op_sel_hi:[1,0]
	v_pk_add_f32 v[80:81], v[80:81], v[140:141]
	v_exp_f32_e32 v70, v70
	v_pk_mul_f32 v[68:69], v[68:69], v[204:205] op_sel_hi:[1,0]
	v_lshl_add_u64 v[156:157], v[156:157], 0, s[6:7]
	v_exp_f32_e32 v71, v71
	v_mul_f32_e32 v176, 0xbfb8aa3b, v146
	v_pk_add_f32 v[70:71], v[70:71], v[140:141]
	v_exp_f32_e32 v72, v72
	v_pk_mul_f32 v[62:63], v[62:63], v[176:177] op_sel_hi:[1,0]
	v_pk_mul_f32 v[64:65], v[64:65], v[176:177] op_sel_hi:[1,0]
	v_exp_f32_e32 v73, v73
	v_pk_mul_f32 v[54:55], v[54:55], v[176:177] op_sel_hi:[1,0]
	v_pk_add_f32 v[72:73], v[72:73], v[140:141]
	v_rcp_f32_e32 v78, v78
	v_pk_mul_f32 v[56:57], v[56:57], v[176:177] op_sel_hi:[1,0]
	v_mul_f32_e32 v206, v146, v146
	v_rcp_f32_e32 v79, v79
	v_pk_mul_f32 v[58:59], v[58:59], v[206:207] op_sel_hi:[1,0]
	v_pk_mul_f32 v[74:75], v[74:75], v[78:79]
	v_rcp_f32_e32 v80, v80
	v_cvt_pk_bf16_f32 v78, v74, v75
	v_pk_mul_f32 v[60:61], v[60:61], v[206:207] op_sel_hi:[1,0]
	v_rcp_f32_e32 v81, v81
	v_pk_mul_f32 v[50:51], v[50:51], v[206:207] op_sel_hi:[1,0]
	v_pk_mul_f32 v[76:77], v[76:77], v[80:81]
	v_rcp_f32_e32 v70, v70
	v_cvt_pk_bf16_f32 v79, v76, v77
	v_pk_mul_f32 v[52:53], v[52:53], v[206:207] op_sel_hi:[1,0]
	v_rcp_f32_e32 v71, v71
	s_mov_b32 s6, 0xdc000
	v_pk_mul_f32 v[66:67], v[66:67], v[70:71]
	v_rcp_f32_e32 v72, v72
	v_cvt_pk_bf16_f32 v80, v66, v67
	v_min_u32_e32 v178, 32, v178
	v_rcp_f32_e32 v73, v73
	v_lshlrev_b64 v[148:149], v178, v[148:149]
	v_pk_mul_f32 v[68:69], v[68:69], v[72:73]
	v_exp_f32_e32 v62, v62
	v_cvt_pk_bf16_f32 v81, v68, v69
	global_store_dwordx4 v[156:157], v[78:81], off
	v_exp_f32_e32 v63, v63
	v_lshl_add_u64 v[156:157], v[156:157], 0, s[6:7]
; __device__ __forceinline__ unsigned pk2(float lo, float hi) { unsigned r; asm("v_cvt_pk_bf16_f32 %0, %1, %2" : "=v"(r) : "v"(lo), "v"(hi)); return r; }
; __device__ __forceinline__ float sigmoidf_(float v) { return __builtin_amdgcn_rcpf(1.0f + fexp(-v)); }
; #define PG8_BAR __builtin_amdgcn_s_barrier()
; template <class Epi, class Sched, bool ALIGN_EPI = true, bool SP2 = true>
; __device__ __forceinline__ void gemm_phase(LAS unsigned char* lds, const Gemm g, const Sched& S, const Epi& E) {
;     ...
;         if constexpr (ALIGN_EPI) { if (wr == 0) PG8_BAR; }
;         const bool keep = E(acc, cur, wr, wc, fr, fq);
;         if (!has_next) break;
;         if (!keep) {
; #pragma unroll
;         for (int a = 0; a < 2; ++a)
; #pragma unroll
;             for (int b = 0; b < 2; ++b)
; #pragma unroll
;                 for (int m = 0; m < 4; ++m)
; #pragma unroll
;                     for (int n = 0; n < 2; ++n) acc[a][b][m][n] = (f32x4){0.f, 0.f, 0.f, 0.f};
;         }
;         cur = nxt; cA = nA; cB = nB; ++ui;
;         if constexpr (ALIGN_EPI) { if (wr == 1) PG8_BAR; }
;     __device__ __forceinline__ bool operator()(f32x4 (&acc)[2][2][4][2], const pg8::Unit& u, int wr, int wc, int fr, int fq) const {
;     ...
;                 const int row = row0 + ai * 128 + m * 16; const float r = rr[ai * 4 + m];
;                 float o[8];
; #pragma unroll
;                 for (int n = 0; n < 2; ++n)
; #pragma unroll
;                     for (int j = 0; j < 4; ++j) { const float gv = acc[ai][0][m][n][j] * r, uv = acc[ai][1][m][n][j] * r; o[n * 4 + j] = gv * sigmoidf_(gv) * uv; }
;                 u32x4 w; w.x = pk2(o[0], o[1]); w.y = pk2(o[2], o[3]); w.z = pk2(o[4], o[5]); w.w = pk2(o[6], o[7]);
;                 *(u32x4*)(act + (size_t)row * FF + col0) = w;
;             }
;         return false;
	v_pk_add_f32 v[62:63], v[62:63], v[140:141]
	v_exp_f32_e32 v64, v64
	v_min_u32_e32 v208, 1, v148
	v_or_b32_e32 v208, v149, v208
	v_exp_f32_e32 v65, v65
	v_cvt_f32_u32_e32 v208, v208
	v_pk_add_f32 v[64:65], v[64:65], v[140:141]
	v_exp_f32_e32 v54, v54
	v_sub_u32_e32 v178, 32, v178
	v_ldexp_f32 v208, v208, v178
	v_exp_f32_e32 v55, v55
	v_mul_f32_e32 v208, 0x33800000, v208
	v_pk_add_f32 v[54:55], v[54:55], v[140:141]
	v_exp_f32_e32 v56, v56
	v_fmamk_f32 v208, v208, 0x3a000000, v218
	s_mov_b32 s6, 0x2c000
	v_exp_f32_e32 v57, v57
	v_ffbh_u32_e32 v194, v145
	v_pk_add_f32 v[56:57], v[56:57], v[140:141]
	v_rcp_f32_e32 v62, v62
	v_min_u32_e32 v194, 32, v194
	v_lshlrev_b64 v[144:145], v194, v[144:145]
	v_rcp_f32_e32 v63, v63
	v_min_u32_e32 v210, 1, v144
	v_pk_mul_f32 v[58:59], v[58:59], v[62:63]
	v_rcp_f32_e32 v64, v64
	v_cvt_pk_bf16_f32 v62, v58, v59
	v_or_b32_e32 v210, v145, v210
	v_rcp_f32_e32 v65, v65
	v_cvt_f32_u32_e32 v210, v210
	v_pk_mul_f32 v[60:61], v[60:61], v[64:65]
	v_rcp_f32_e32 v54, v54
	v_cvt_pk_bf16_f32 v63, v60, v61
	v_sub_u32_e32 v194, 32, v194
	v_rcp_f32_e32 v55, v55
	v_ldexp_f32 v210, v210, v194
	v_pk_mul_f32 v[50:51], v[50:51], v[54:55]
	v_rcp_f32_e32 v56, v56
	v_cvt_pk_bf16_f32 v64, v50, v51
	v_mul_f32_e32 v210, 0x33800000, v210
	v_rcp_f32_e32 v57, v57
	v_fmamk_f32 v210, v210, 0x3a000000, v218
	v_pk_mul_f32 v[52:53], v[52:53], v[56:57]
	v_rsq_f32_e32 v148, v208
	v_cvt_pk_bf16_f32 v65, v52, v53
	global_store_dwordx4 v[156:157], v[62:65], off
	v_rsq_f32_e32 v144, v210
	v_mul_f32_e32 v178, 0xbfb8aa3b, v148
	v_pk_mul_f32 v[46:47], v[46:47], v[178:179] op_sel_hi:[1,0]
	v_pk_mul_f32 v[48:49], v[48:49], v[178:179] op_sel_hi:[1,0]
	v_exp_f32_e32 v46, v46
	v_pk_mul_f32 v[38:39], v[38:39], v[178:179] op_sel_hi:[1,0]
	v_pk_mul_f32 v[40:41], v[40:41], v[178:179] op_sel_hi:[1,0]
	v_exp_f32_e32 v47, v47
	v_mul_f32_e32 v208, v148, v148
	v_pk_add_f32 v[46:47], v[46:47], v[140:141]
	v_exp_f32_e32 v48, v48
	v_pk_mul_f32 v[42:43], v[42:43], v[208:209] op_sel_hi:[1,0]
	v_pk_mul_f32 v[44:45], v[44:45], v[208:209] op_sel_hi:[1,0]
	v_exp_f32_e32 v49, v49
	v_pk_mul_f32 v[34:35], v[34:35], v[208:209] op_sel_hi:[1,0]
	v_pk_add_f32 v[48:49], v[48:49], v[140:141]
	v_exp_f32_e32 v38, v38
	v_pk_mul_f32 v[36:37], v[36:37], v[208:209] op_sel_hi:[1,0]
	v_lshl_add_u64 v[156:157], v[156:157], 0, s[6:7]
	v_exp_f32_e32 v39, v39
	v_mul_f32_e32 v194, 0xbfb8aa3b, v144
	v_pk_add_f32 v[38:39], v[38:39], v[140:141]
	v_exp_f32_e32 v40, v40
	v_pk_mul_f32 v[30:31], v[30:31], v[194:195] op_sel_hi:[1,0]
	v_pk_mul_f32 v[32:33], v[32:33], v[194:195] op_sel_hi:[1,0]
	v_exp_f32_e32 v41, v41
	v_pk_mul_f32 v[22:23], v[22:23], v[194:195] op_sel_hi:[1,0]
	v_pk_add_f32 v[40:41], v[40:41], v[140:141]
	v_rcp_f32_e32 v46, v46
	v_pk_mul_f32 v[24:25], v[24:25], v[194:195] op_sel_hi:[1,0]
	v_mul_f32_e32 v210, v144, v144
	v_rcp_f32_e32 v47, v47
	v_pk_mul_f32 v[26:27], v[26:27], v[210:211] op_sel_hi:[1,0]
	v_pk_mul_f32 v[42:43], v[42:43], v[46:47]
	v_rcp_f32_e32 v48, v48
	v_cvt_pk_bf16_f32 v46, v42, v43
	v_pk_mul_f32 v[28:29], v[28:29], v[210:211] op_sel_hi:[1,0]
	v_rcp_f32_e32 v49, v49
	v_pk_mul_f32 v[18:19], v[18:19], v[210:211] op_sel_hi:[1,0]
	v_pk_mul_f32 v[44:45], v[44:45], v[48:49]
	v_rcp_f32_e32 v38, v38
	v_cvt_pk_bf16_f32 v47, v44, v45
	v_pk_mul_f32 v[20:21], v[20:21], v[210:211] op_sel_hi:[1,0]
	v_rcp_f32_e32 v39, v39
	v_ffbh_u32_e32 v196, v143
	v_pk_mul_f32 v[34:35], v[34:35], v[38:39]
	v_rcp_f32_e32 v40, v40
	v_cvt_pk_bf16_f32 v48, v34, v35
	v_min_u32_e32 v196, 32, v196
	v_rcp_f32_e32 v41, v41
	v_lshlrev_b64 v[142:143], v196, v[142:143]
	v_pk_mul_f32 v[36:37], v[36:37], v[40:41]
	v_exp_f32_e32 v30, v30
	v_cvt_pk_bf16_f32 v49, v36, v37
	global_store_dwordx4 v[156:157], v[46:49], off
	v_exp_f32_e32 v31, v31
	v_lshl_add_u64 v[156:157], v[156:157], 0, s[6:7]
	v_pk_add_f32 v[30:31], v[30:31], v[140:141]
	v_exp_f32_e32 v32, v32
	v_min_u32_e32 v212, 1, v142
	v_or_b32_e32 v212, v143, v212
	v_exp_f32_e32 v33, v33
	v_cvt_f32_u32_e32 v212, v212
	v_pk_add_f32 v[32:33], v[32:33], v[140:141]
	v_exp_f32_e32 v22, v22
	v_sub_u32_e32 v196, 32, v196
	v_ldexp_f32 v212, v212, v196
	v_exp_f32_e32 v23, v23
	v_mul_f32_e32 v212, 0x33800000, v212
	v_pk_add_f32 v[22:23], v[22:23], v[140:141]
	v_exp_f32_e32 v24, v24
	v_fmamk_f32 v212, v212, 0x3a000000, v218
	v_exp_f32_e32 v25, v25
	v_rcp_f32_e32 v30, v30
	v_pk_add_f32 v[24:25], v[24:25], v[140:141]
	v_rcp_f32_e32 v31, v31
	v_rcp_f32_e32 v32, v32
	v_pk_mul_f32 v[26:27], v[26:27], v[30:31]
	v_rcp_f32_e32 v33, v33
	v_cvt_pk_bf16_f32 v30, v26, v27
	v_pk_mul_f32 v[28:29], v[28:29], v[32:33]
	v_rcp_f32_e32 v22, v22
	v_cvt_pk_bf16_f32 v31, v28, v29
	v_rcp_f32_e32 v23, v23
	v_rcp_f32_e32 v24, v24
	v_pk_mul_f32 v[18:19], v[18:19], v[22:23]
	v_rcp_f32_e32 v25, v25
	v_cvt_pk_bf16_f32 v32, v18, v19
	v_pk_mul_f32 v[20:21], v[20:21], v[24:25]
	v_rsq_f32_e32 v142, v212
	v_cvt_pk_bf16_f32 v33, v20, v21
	global_store_dwordx4 v[156:157], v[30:33], off
	v_mul_f32_e32 v196, 0xbfb8aa3b, v142
	v_pk_mul_f32 v[14:15], v[14:15], v[196:197] op_sel_hi:[1,0]
	v_pk_mul_f32 v[16:17], v[16:17], v[196:197] op_sel_hi:[1,0]
	v_exp_f32_e32 v14, v14
	v_pk_mul_f32 v[6:7], v[6:7], v[196:197] op_sel_hi:[1,0]
	v_pk_mul_f32 v[8:9], v[8:9], v[196:197] op_sel_hi:[1,0]
	v_exp_f32_e32 v15, v15
	v_mul_f32_e32 v212, v142, v142
	v_pk_add_f32 v[14:15], v[14:15], v[140:141]
	v_exp_f32_e32 v16, v16
	v_pk_mul_f32 v[10:11], v[10:11], v[212:213] op_sel_hi:[1,0]
	v_pk_mul_f32 v[12:13], v[12:13], v[212:213] op_sel_hi:[1,0]
	v_exp_f32_e32 v17, v17
	v_pk_mul_f32 v[2:3], v[2:3], v[212:213] op_sel_hi:[1,0]
	v_pk_add_f32 v[16:17], v[16:17], v[140:141]
	v_exp_f32_e32 v6, v6
	v_pk_mul_f32 v[4:5], v[4:5], v[212:213] op_sel_hi:[1,0]
	v_lshl_add_u64 v[156:157], v[156:157], 0, s[6:7]
	v_exp_f32_e32 v7, v7
	v_exp_f32_e32 v8, v8
	v_pk_add_f32 v[6:7], v[6:7], v[140:141]
	v_exp_f32_e32 v9, v9
	v_rcp_f32_e32 v14, v14
	v_pk_add_f32 v[8:9], v[8:9], v[140:141]
	v_rcp_f32_e32 v15, v15
	v_rcp_f32_e32 v16, v16
	v_pk_mul_f32 v[10:11], v[10:11], v[14:15]
	v_rcp_f32_e32 v17, v17
	v_cvt_pk_bf16_f32 v14, v10, v11
	v_pk_mul_f32 v[12:13], v[12:13], v[16:17]
	v_rcp_f32_e32 v6, v6
	v_cvt_pk_bf16_f32 v15, v12, v13
	v_rcp_f32_e32 v7, v7
	v_rcp_f32_e32 v8, v8
	v_pk_mul_f32 v[2:3], v[2:3], v[6:7]
	v_rcp_f32_e32 v9, v9
	v_cvt_pk_bf16_f32 v16, v2, v3
	v_pk_mul_f32 v[4:5], v[4:5], v[8:9]
	s_nop 0
	v_cvt_pk_bf16_f32 v17, v4, v5
	global_store_dwordx4 v[156:157], v[14:17], off
	s_mov_b64 s[6:7], -1
	s_andn2_b64 vcc, exec, s[0:1]
	s_cbranch_vccnz .LBB0_90
	s_andn2_b64 vcc, exec, s[4:5]
	s_cbranch_vccnz .LBB0_89
	s_barrier
	s_branch .LBB0_89

; __device__ __forceinline__ unsigned pk2(float lo, float hi) { unsigned r; asm("v_cvt_pk_bf16_f32 %0, %1, %2" : "=v"(r) : "v"(lo), "v"(hi)); return r; }
; __device__ __forceinline__ float sigmoidf_(float v) { return __builtin_amdgcn_rcpf(1.0f + fexp(-v)); }
; __device__ __forceinline__ void row_rstd8(const ssq_t* ss, int row0, float (&r)[8]) {
;     ssq_t sv[8];
; #pragma unroll
;     for (int k = 0; k < 8; ++k) sv[k] = ss[row0 + (k >> 2) * 128 + (k & 3) * 16];
;     asm volatile("" ::: "memory");
; #pragma unroll
;     for (int k = 0; k < 8; ++k) r[k] = rsqrtf((float)sv[k] * (1.0f / SSQ_SCALE) * (1.0f / D) + EPS);
; }
;     __device__ __forceinline__ bool operator()(f32x4 (&acc)[2][2][4][2], const pg8::Unit& u, int wr, int wc, int fr, int fq) const {
;         const int row0 = u.pm * 256 + wr * 64 + fr, col0 = u.pn * 128 + wc * 32 + 8 * fq;
;         float rr[8]; row_rstd8(ss, row0, rr);
; #pragma unroll
;         for (int ai = 0; ai < 2; ++ai)
; #pragma unroll
;             for (int m = 0; m < 4; ++m) {
;                 const int row = row0 + ai * 128 + m * 16; const float r = rr[ai * 4 + m];
;                 float o[8];
; #pragma unroll
;                 for (int n = 0; n < 2; ++n)
; #pragma unroll
;                     for (int j = 0; j < 4; ++j) { const float gv = acc[ai][0][m][n][j] * r, uv = acc[ai][1][m][n][j] * r; o[n * 4 + j] = gv * sigmoidf_(gv) * uv; }
;                 u32x4 w; w.x = pk2(o[0], o[1]); w.y = pk2(o[2], o[3]); w.z = pk2(o[4], o[5]); w.w = pk2(o[6], o[7]);
;                 *(u32x4*)(act + (size_t)row * FF + col0) = w;
.LBB0_874:
	v_lshl_add_u32 v140, s57, 8, v151
	v_ashrrev_i32_e32 v141, 31, v140
	v_lshl_or_b32 v156, s56, 7, v155
	v_ashrrev_i32_e32 v157, 31, v156
	v_lshl_add_u64 v[142:143], v[140:141], 3, s[0:1]
	global_load_dwordx2 v[160:161], v[142:143], off
	global_load_dwordx2 v[162:163], v[142:143], off offset:128
	global_load_dwordx2 v[164:165], v[142:143], off offset:256
	global_load_dwordx2 v[166:167], v[142:143], off offset:384
	global_load_dwordx2 v[146:147], v[142:143], off offset:1024
	global_load_dwordx2 v[148:149], v[142:143], off offset:1152
	global_load_dwordx2 v[144:145], v[142:143], off offset:1280
	s_nop 0
	global_load_dwordx2 v[142:143], v[142:143], off offset:1408
	v_lshlrev_b64 v[156:157], 1, v[156:157]
	v_lshl_add_u64 v[156:157], v[156:157], 0, s[90:91]
	v_mad_i64_i32 v[156:157], s[4:5], v140, s37, v[156:157]
	v_mov_b32_e32 v140, 1.0
	v_mov_b32_e32 v141, 1.0
	v_pk_mul_f32 v[122:123], v[122:123], v[126:127]
	v_pk_mul_f32 v[124:125], v[124:125], v[128:129]
	v_pk_mul_f32 v[114:115], v[114:115], v[118:119]
	v_pk_mul_f32 v[116:117], v[116:117], v[120:121]
	v_pk_mul_f32 v[106:107], v[106:107], v[110:111]
	v_pk_mul_f32 v[108:109], v[108:109], v[112:113]
	v_pk_mul_f32 v[98:99], v[98:99], v[102:103]
	v_pk_mul_f32 v[100:101], v[100:101], v[104:105]
	v_pk_mul_f32 v[90:91], v[90:91], v[94:95]
	v_pk_mul_f32 v[92:93], v[92:93], v[96:97]
	v_pk_mul_f32 v[82:83], v[82:83], v[86:87]
	v_pk_mul_f32 v[84:85], v[84:85], v[88:89]
	v_pk_mul_f32 v[74:75], v[74:75], v[78:79]
	v_pk_mul_f32 v[76:77], v[76:77], v[80:81]
	v_pk_mul_f32 v[66:67], v[66:67], v[70:71]
	v_pk_mul_f32 v[68:69], v[68:69], v[72:73]
	v_pk_mul_f32 v[58:59], v[58:59], v[62:63]
	v_pk_mul_f32 v[60:61], v[60:61], v[64:65]
	v_pk_mul_f32 v[50:51], v[50:51], v[54:55]
	v_pk_mul_f32 v[52:53], v[52:53], v[56:57]
	v_pk_mul_f32 v[42:43], v[42:43], v[46:47]
	v_pk_mul_f32 v[44:45], v[44:45], v[48:49]
	v_pk_mul_f32 v[34:35], v[34:35], v[38:39]
	v_pk_mul_f32 v[36:37], v[36:37], v[40:41]
	v_pk_mul_f32 v[26:27], v[26:27], v[30:31]
	v_pk_mul_f32 v[28:29], v[28:29], v[32:33]
	v_pk_mul_f32 v[18:19], v[18:19], v[22:23]
	v_pk_mul_f32 v[20:21], v[20:21], v[24:25]
	v_pk_mul_f32 v[10:11], v[10:11], v[14:15]
	v_pk_mul_f32 v[12:13], v[12:13], v[16:17]
	v_pk_mul_f32 v[2:3], v[2:3], v[6:7]
	v_pk_mul_f32 v[4:5], v[4:5], v[8:9]
	s_mov_b32 s4, 0x2c000
	s_mov_b32 s5, 0
	s_waitcnt vmcnt(0)
	v_ffbh_u32_e32 v168, v161
	v_min_u32_e32 v168, 32, v168
	v_lshlrev_b64 v[160:161], v168, v[160:161]
	v_min_u32_e32 v198, 1, v160
	v_or_b32_e32 v198, v161, v198
	v_cvt_f32_u32_e32 v198, v198
	v_sub_u32_e32 v168, 32, v168
	v_ldexp_f32 v198, v198, v168
	v_mul_f32_e32 v198, 0x33800000, v198
	v_fmamk_f32 v198, v198, 0x3a000000, v218
	v_rsq_f32_e32 v160, v198
	v_ffbh_u32_e32 v170, v163
	v_mul_f32_e32 v168, 0xbfb8aa3b, v160
	v_pk_mul_f32 v[126:127], v[126:127], v[168:169] op_sel_hi:[1,0]
	v_pk_mul_f32 v[128:129], v[128:129], v[168:169] op_sel_hi:[1,0]
	v_exp_f32_e32 v126, v126
	v_pk_mul_f32 v[118:119], v[118:119], v[168:169] op_sel_hi:[1,0]
	v_pk_mul_f32 v[120:121], v[120:121], v[168:169] op_sel_hi:[1,0]
	v_exp_f32_e32 v127, v127
	v_mul_f32_e32 v198, v160, v160
	v_pk_add_f32 v[126:127], v[126:127], v[140:141]
	v_exp_f32_e32 v128, v128
	v_pk_mul_f32 v[122:123], v[122:123], v[198:199] op_sel_hi:[1,0]
	v_pk_mul_f32 v[124:125], v[124:125], v[198:199] op_sel_hi:[1,0]
	v_exp_f32_e32 v129, v129
	v_pk_mul_f32 v[114:115], v[114:115], v[198:199] op_sel_hi:[1,0]
	v_pk_add_f32 v[128:129], v[128:129], v[140:141]
	v_exp_f32_e32 v118, v118
	v_pk_mul_f32 v[116:117], v[116:117], v[198:199] op_sel_hi:[1,0]
	v_min_u32_e32 v170, 32, v170
	v_exp_f32_e32 v119, v119
	v_lshlrev_b64 v[162:163], v170, v[162:163]
	v_pk_add_f32 v[118:119], v[118:119], v[140:141]
	v_exp_f32_e32 v120, v120
	v_min_u32_e32 v200, 1, v162
	v_or_b32_e32 v200, v163, v200
	v_exp_f32_e32 v121, v121
	v_cvt_f32_u32_e32 v200, v200
	v_pk_add_f32 v[120:121], v[120:121], v[140:141]
	v_rcp_f32_e32 v126, v126
	v_sub_u32_e32 v170, 32, v170
	v_ldexp_f32 v200, v200, v170
	v_rcp_f32_e32 v127, v127
	v_mul_f32_e32 v200, 0x33800000, v200
	v_pk_mul_f32 v[122:123], v[122:123], v[126:127]
	v_rcp_f32_e32 v128, v128
	v_cvt_pk_bf16_f32 v126, v122, v123
	v_fmamk_f32 v200, v200, 0x3a000000, v218
	v_rcp_f32_e32 v129, v129
	v_ffbh_u32_e32 v172, v165
	v_pk_mul_f32 v[124:125], v[124:125], v[128:129]
	v_rcp_f32_e32 v118, v118
	v_cvt_pk_bf16_f32 v127, v124, v125
	v_min_u32_e32 v172, 32, v172
	v_rcp_f32_e32 v119, v119
	v_lshlrev_b64 v[164:165], v172, v[164:165]
	v_pk_mul_f32 v[114:115], v[114:115], v[118:119]
	v_rcp_f32_e32 v120, v120
	v_cvt_pk_bf16_f32 v128, v114, v115
	v_min_u32_e32 v202, 1, v164
	v_rcp_f32_e32 v121, v121
	v_or_b32_e32 v202, v165, v202
	v_pk_mul_f32 v[116:117], v[116:117], v[120:121]
	v_rsq_f32_e32 v162, v200
	v_cvt_pk_bf16_f32 v129, v116, v117
	global_store_dwordx4 v[156:157], v[126:129], off
	v_mul_f32_e32 v170, 0xbfb8aa3b, v162
	v_pk_mul_f32 v[110:111], v[110:111], v[170:171] op_sel_hi:[1,0]
	v_pk_mul_f32 v[112:113], v[112:113], v[170:171] op_sel_hi:[1,0]
	v_exp_f32_e32 v110, v110
	v_pk_mul_f32 v[102:103], v[102:103], v[170:171] op_sel_hi:[1,0]
	v_pk_mul_f32 v[104:105], v[104:105], v[170:171] op_sel_hi:[1,0]
	v_exp_f32_e32 v111, v111
	v_mul_f32_e32 v200, v162, v162
	v_pk_add_f32 v[110:111], v[110:111], v[140:141]
	v_exp_f32_e32 v112, v112
	v_pk_mul_f32 v[106:107], v[106:107], v[200:201] op_sel_hi:[1,0]
	v_pk_mul_f32 v[108:109], v[108:109], v[200:201] op_sel_hi:[1,0]
	v_exp_f32_e32 v113, v113
	v_pk_mul_f32 v[98:99], v[98:99], v[200:201] op_sel_hi:[1,0]
	v_pk_add_f32 v[112:113], v[112:113], v[140:141]
	v_exp_f32_e32 v102, v102
	v_pk_mul_f32 v[100:101], v[100:101], v[200:201] op_sel_hi:[1,0]
; __device__ __forceinline__ unsigned pk2(float lo, float hi) { unsigned r; asm("v_cvt_pk_bf16_f32 %0, %1, %2" : "=v"(r) : "v"(lo), "v"(hi)); return r; }
; __device__ __forceinline__ float sigmoidf_(float v) { return __builtin_amdgcn_rcpf(1.0f + fexp(-v)); }
;     __device__ __forceinline__ bool operator()(f32x4 (&acc)[2][2][4][2], const pg8::Unit& u, int wr, int wc, int fr, int fq) const {
;     ...
;                 const int row = row0 + ai * 128 + m * 16; const float r = rr[ai * 4 + m];
;                 float o[8];
; #pragma unroll
;                 for (int n = 0; n < 2; ++n)
; #pragma unroll
;                     for (int j = 0; j < 4; ++j) { const float gv = acc[ai][0][m][n][j] * r, uv = acc[ai][1][m][n][j] * r; o[n * 4 + j] = gv * sigmoidf_(gv) * uv; }
;                 u32x4 w; w.x = pk2(o[0], o[1]); w.y = pk2(o[2], o[3]); w.z = pk2(o[4], o[5]); w.w = pk2(o[6], o[7]);
;                 *(u32x4*)(act + (size_t)row * FF + col0) = w;
	v_lshl_add_u64 v[156:157], v[156:157], 0, s[4:5]
	v_exp_f32_e32 v103, v103
	v_cvt_f32_u32_e32 v202, v202
	v_pk_add_f32 v[102:103], v[102:103], v[140:141]
	v_exp_f32_e32 v104, v104
	v_sub_u32_e32 v172, 32, v172
	v_ldexp_f32 v202, v202, v172
	v_exp_f32_e32 v105, v105
	v_mul_f32_e32 v202, 0x33800000, v202
	v_pk_add_f32 v[104:105], v[104:105], v[140:141]
	v_rcp_f32_e32 v110, v110
	v_fmamk_f32 v202, v202, 0x3a000000, v218
	v_ffbh_u32_e32 v174, v167
	v_rcp_f32_e32 v111, v111
	v_min_u32_e32 v174, 32, v174
	v_pk_mul_f32 v[106:107], v[106:107], v[110:111]
	v_rcp_f32_e32 v112, v112
	v_cvt_pk_bf16_f32 v110, v106, v107
	v_lshlrev_b64 v[166:167], v174, v[166:167]
	v_rcp_f32_e32 v113, v113
	v_min_u32_e32 v204, 1, v166
	v_pk_mul_f32 v[108:109], v[108:109], v[112:113]
	v_rcp_f32_e32 v102, v102
	v_cvt_pk_bf16_f32 v111, v108, v109
	v_or_b32_e32 v204, v167, v204
	v_rcp_f32_e32 v103, v103
	v_cvt_f32_u32_e32 v204, v204
	v_pk_mul_f32 v[98:99], v[98:99], v[102:103]
	v_rcp_f32_e32 v104, v104
	v_cvt_pk_bf16_f32 v112, v98, v99
	v_sub_u32_e32 v174, 32, v174
	v_rcp_f32_e32 v105, v105
	v_ldexp_f32 v204, v204, v174
	v_pk_mul_f32 v[100:101], v[100:101], v[104:105]
	v_rsq_f32_e32 v164, v202
	v_cvt_pk_bf16_f32 v113, v100, v101
	global_store_dwordx4 v[156:157], v[110:113], off
	v_mul_f32_e32 v172, 0xbfb8aa3b, v164
	v_pk_mul_f32 v[94:95], v[94:95], v[172:173] op_sel_hi:[1,0]
	v_pk_mul_f32 v[96:97], v[96:97], v[172:173] op_sel_hi:[1,0]
	v_exp_f32_e32 v94, v94
	v_pk_mul_f32 v[86:87], v[86:87], v[172:173] op_sel_hi:[1,0]
	v_pk_mul_f32 v[88:89], v[88:89], v[172:173] op_sel_hi:[1,0]
	v_exp_f32_e32 v95, v95
	v_mul_f32_e32 v202, v164, v164
	v_pk_add_f32 v[94:95], v[94:95], v[140:141]
	v_exp_f32_e32 v96, v96
	v_pk_mul_f32 v[90:91], v[90:91], v[202:203] op_sel_hi:[1,0]
	v_pk_mul_f32 v[92:93], v[92:93], v[202:203] op_sel_hi:[1,0]
	v_exp_f32_e32 v97, v97
	v_pk_mul_f32 v[82:83], v[82:83], v[202:203] op_sel_hi:[1,0]
	v_pk_add_f32 v[96:97], v[96:97], v[140:141]
	v_exp_f32_e32 v86, v86
	v_pk_mul_f32 v[84:85], v[84:85], v[202:203] op_sel_hi:[1,0]
	v_lshl_add_u64 v[156:157], v[156:157], 0, s[4:5]
	v_exp_f32_e32 v87, v87
	v_mul_f32_e32 v204, 0x33800000, v204
	v_pk_add_f32 v[86:87], v[86:87], v[140:141]
	v_exp_f32_e32 v88, v88
	v_fmamk_f32 v204, v204, 0x3a000000, v218
	v_ffbh_u32_e32 v176, v147
	v_exp_f32_e32 v89, v89
	v_min_u32_e32 v176, 32, v176
	v_pk_add_f32 v[88:89], v[88:89], v[140:141]
	v_rcp_f32_e32 v94, v94
	v_lshlrev_b64 v[146:147], v176, v[146:147]
	v_min_u32_e32 v206, 1, v146
	v_rcp_f32_e32 v95, v95
	v_or_b32_e32 v206, v147, v206
	v_pk_mul_f32 v[90:91], v[90:91], v[94:95]
	v_rcp_f32_e32 v96, v96
	v_cvt_pk_bf16_f32 v94, v90, v91
	v_cvt_f32_u32_e32 v206, v206
	v_rcp_f32_e32 v97, v97
	v_sub_u32_e32 v176, 32, v176
	v_pk_mul_f32 v[92:93], v[92:93], v[96:97]
	v_rcp_f32_e32 v86, v86
	v_cvt_pk_bf16_f32 v95, v92, v93
	v_ldexp_f32 v206, v206, v176
	v_rcp_f32_e32 v87, v87
	v_mul_f32_e32 v206, 0x33800000, v206
	v_pk_mul_f32 v[82:83], v[82:83], v[86:87]
	v_rcp_f32_e32 v88, v88
	v_cvt_pk_bf16_f32 v96, v82, v83
	v_fmamk_f32 v206, v206, 0x3a000000, v218
	v_rcp_f32_e32 v89, v89
	v_ffbh_u32_e32 v178, v149
	v_pk_mul_f32 v[84:85], v[84:85], v[88:89]
	v_rsq_f32_e32 v166, v204
	v_cvt_pk_bf16_f32 v97, v84, v85
	global_store_dwordx4 v[156:157], v[94:97], off
	v_rsq_f32_e32 v146, v206
	v_mul_f32_e32 v174, 0xbfb8aa3b, v166
	v_pk_mul_f32 v[78:79], v[78:79], v[174:175] op_sel_hi:[1,0]
	v_pk_mul_f32 v[80:81], v[80:81], v[174:175] op_sel_hi:[1,0]
	v_exp_f32_e32 v78, v78
	v_pk_mul_f32 v[70:71], v[70:71], v[174:175] op_sel_hi:[1,0]
	v_pk_mul_f32 v[72:73], v[72:73], v[174:175] op_sel_hi:[1,0]
	v_exp_f32_e32 v79, v79
	v_mul_f32_e32 v204, v166, v166
	v_pk_add_f32 v[78:79], v[78:79], v[140:141]
	v_exp_f32_e32 v80, v80
	v_pk_mul_f32 v[74:75], v[74:75], v[204:205] op_sel_hi:[1,0]
	v_pk_mul_f32 v[76:77], v[76:77], v[204:205] op_sel_hi:[1,0]
	v_exp_f32_e32 v81, v81
	v_pk_mul_f32 v[66:67], v[66:67], v[204:205] op_sel_hi:[1,0]
	v_pk_add_f32 v[80:81], v[80:81], v[140:141]
	v_exp_f32_e32 v70, v70
	v_pk_mul_f32 v[68:69], v[68:69], v[204:205] op_sel_hi:[1,0]
	v_lshl_add_u64 v[156:157], v[156:157], 0, s[4:5]
	v_exp_f32_e32 v71, v71
	v_mul_f32_e32 v176, 0xbfb8aa3b, v146
	v_pk_add_f32 v[70:71], v[70:71], v[140:141]
	v_exp_f32_e32 v72, v72
	v_pk_mul_f32 v[62:63], v[62:63], v[176:177] op_sel_hi:[1,0]
	v_pk_mul_f32 v[64:65], v[64:65], v[176:177] op_sel_hi:[1,0]
	v_exp_f32_e32 v73, v73
	v_pk_mul_f32 v[54:55], v[54:55], v[176:177] op_sel_hi:[1,0]
	v_pk_add_f32 v[72:73], v[72:73], v[140:141]
	v_rcp_f32_e32 v78, v78
	v_pk_mul_f32 v[56:57], v[56:57], v[176:177] op_sel_hi:[1,0]
	v_mul_f32_e32 v206, v146, v146
	v_rcp_f32_e32 v79, v79
	v_pk_mul_f32 v[58:59], v[58:59], v[206:207] op_sel_hi:[1,0]
	v_pk_mul_f32 v[74:75], v[74:75], v[78:79]
	v_rcp_f32_e32 v80, v80
	v_cvt_pk_bf16_f32 v78, v74, v75
	v_pk_mul_f32 v[60:61], v[60:61], v[206:207] op_sel_hi:[1,0]
	v_rcp_f32_e32 v81, v81
	v_pk_mul_f32 v[50:51], v[50:51], v[206:207] op_sel_hi:[1,0]
	v_pk_mul_f32 v[76:77], v[76:77], v[80:81]
	v_rcp_f32_e32 v70, v70
	v_cvt_pk_bf16_f32 v79, v76, v77
	v_pk_mul_f32 v[52:53], v[52:53], v[206:207] op_sel_hi:[1,0]
	v_rcp_f32_e32 v71, v71
	s_mov_b32 s4, 0xdc000
	v_pk_mul_f32 v[66:67], v[66:67], v[70:71]
	v_rcp_f32_e32 v72, v72
	v_cvt_pk_bf16_f32 v80, v66, v67
	v_min_u32_e32 v178, 32, v178
	v_rcp_f32_e32 v73, v73
	v_lshlrev_b64 v[148:149], v178, v[148:149]
	v_pk_mul_f32 v[68:69], v[68:69], v[72:73]
	v_exp_f32_e32 v62, v62
	v_cvt_pk_bf16_f32 v81, v68, v69
	global_store_dwordx4 v[156:157], v[78:81], off
	v_exp_f32_e32 v63, v63
	v_lshl_add_u64 v[156:157], v[156:157], 0, s[4:5]
	v_pk_add_f32 v[62:63], v[62:63], v[140:141]
	v_exp_f32_e32 v64, v64
	v_min_u32_e32 v208, 1, v148
; __device__ __forceinline__ unsigned pk2(float lo, float hi) { unsigned r; asm("v_cvt_pk_bf16_f32 %0, %1, %2" : "=v"(r) : "v"(lo), "v"(hi)); return r; }
; __device__ __forceinline__ float sigmoidf_(float v) { return __builtin_amdgcn_rcpf(1.0f + fexp(-v)); }
; #define PG8_BAR __builtin_amdgcn_s_barrier()
; template <class Epi, class Sched, bool ALIGN_EPI = true, bool SP2 = true>
; __device__ __forceinline__ void gemm_phase(LAS unsigned char* lds, const Gemm g, const Sched& S, const Epi& E) {
;     ...
;         if constexpr (ALIGN_EPI) { if (wr == 0) PG8_BAR; }
;         const bool keep = E(acc, cur, wr, wc, fr, fq);
;         if (!has_next) break;
;         if (!keep) {
; #pragma unroll
;         for (int a = 0; a < 2; ++a)
; #pragma unroll
;             for (int b = 0; b < 2; ++b)
; #pragma unroll
;                 for (int m = 0; m < 4; ++m)
; #pragma unroll
;                     for (int n = 0; n < 2; ++n) acc[a][b][m][n] = (f32x4){0.f, 0.f, 0.f, 0.f};
;         }
;         cur = nxt; cA = nA; cB = nB; ++ui;
;         if constexpr (ALIGN_EPI) { if (wr == 1) PG8_BAR; }
;     __device__ __forceinline__ bool operator()(f32x4 (&acc)[2][2][4][2], const pg8::Unit& u, int wr, int wc, int fr, int fq) const {
;     ...
;                 const int row = row0 + ai * 128 + m * 16; const float r = rr[ai * 4 + m];
;                 float o[8];
; #pragma unroll
;                 for (int n = 0; n < 2; ++n)
; #pragma unroll
;                     for (int j = 0; j < 4; ++j) { const float gv = acc[ai][0][m][n][j] * r, uv = acc[ai][1][m][n][j] * r; o[n * 4 + j] = gv * sigmoidf_(gv) * uv; }
;                 u32x4 w; w.x = pk2(o[0], o[1]); w.y = pk2(o[2], o[3]); w.z = pk2(o[4], o[5]); w.w = pk2(o[6], o[7]);
;                 *(u32x4*)(act + (size_t)row * FF + col0) = w;
;             }
;         return false;
	v_or_b32_e32 v208, v149, v208
	v_exp_f32_e32 v65, v65
	v_cvt_f32_u32_e32 v208, v208
	v_pk_add_f32 v[64:65], v[64:65], v[140:141]
	v_exp_f32_e32 v54, v54
	v_sub_u32_e32 v178, 32, v178
	v_ldexp_f32 v208, v208, v178
	v_exp_f32_e32 v55, v55
	v_mul_f32_e32 v208, 0x33800000, v208
	v_pk_add_f32 v[54:55], v[54:55], v[140:141]
	v_exp_f32_e32 v56, v56
	v_fmamk_f32 v208, v208, 0x3a000000, v218
	s_mov_b32 s4, 0x2c000
	v_exp_f32_e32 v57, v57
	v_ffbh_u32_e32 v194, v145
	v_pk_add_f32 v[56:57], v[56:57], v[140:141]
	v_rcp_f32_e32 v62, v62
	v_min_u32_e32 v194, 32, v194
	v_lshlrev_b64 v[144:145], v194, v[144:145]
	v_rcp_f32_e32 v63, v63
	v_min_u32_e32 v210, 1, v144
	v_pk_mul_f32 v[58:59], v[58:59], v[62:63]
	v_rcp_f32_e32 v64, v64
	v_cvt_pk_bf16_f32 v62, v58, v59
	v_or_b32_e32 v210, v145, v210
	v_rcp_f32_e32 v65, v65
	v_cvt_f32_u32_e32 v210, v210
	v_pk_mul_f32 v[60:61], v[60:61], v[64:65]
	v_rcp_f32_e32 v54, v54
	v_cvt_pk_bf16_f32 v63, v60, v61
	v_sub_u32_e32 v194, 32, v194
	v_rcp_f32_e32 v55, v55
	v_ldexp_f32 v210, v210, v194
	v_pk_mul_f32 v[50:51], v[50:51], v[54:55]
	v_rcp_f32_e32 v56, v56
	v_cvt_pk_bf16_f32 v64, v50, v51
	v_mul_f32_e32 v210, 0x33800000, v210
	v_rcp_f32_e32 v57, v57
	v_fmamk_f32 v210, v210, 0x3a000000, v218
	v_pk_mul_f32 v[52:53], v[52:53], v[56:57]
	v_rsq_f32_e32 v148, v208
	v_cvt_pk_bf16_f32 v65, v52, v53
	global_store_dwordx4 v[156:157], v[62:65], off
	v_rsq_f32_e32 v144, v210
	v_mul_f32_e32 v178, 0xbfb8aa3b, v148
	v_pk_mul_f32 v[46:47], v[46:47], v[178:179] op_sel_hi:[1,0]
	v_pk_mul_f32 v[48:49], v[48:49], v[178:179] op_sel_hi:[1,0]
	v_exp_f32_e32 v46, v46
	v_pk_mul_f32 v[38:39], v[38:39], v[178:179] op_sel_hi:[1,0]
	v_pk_mul_f32 v[40:41], v[40:41], v[178:179] op_sel_hi:[1,0]
	v_exp_f32_e32 v47, v47
	v_mul_f32_e32 v208, v148, v148
	v_pk_add_f32 v[46:47], v[46:47], v[140:141]
	v_exp_f32_e32 v48, v48
	v_pk_mul_f32 v[42:43], v[42:43], v[208:209] op_sel_hi:[1,0]
	v_pk_mul_f32 v[44:45], v[44:45], v[208:209] op_sel_hi:[1,0]
	v_exp_f32_e32 v49, v49
	v_pk_mul_f32 v[34:35], v[34:35], v[208:209] op_sel_hi:[1,0]
	v_pk_add_f32 v[48:49], v[48:49], v[140:141]
	v_exp_f32_e32 v38, v38
	v_pk_mul_f32 v[36:37], v[36:37], v[208:209] op_sel_hi:[1,0]
	v_lshl_add_u64 v[156:157], v[156:157], 0, s[4:5]
	v_exp_f32_e32 v39, v39
	v_mul_f32_e32 v194, 0xbfb8aa3b, v144
	v_pk_add_f32 v[38:39], v[38:39], v[140:141]
	v_exp_f32_e32 v40, v40
	v_pk_mul_f32 v[30:31], v[30:31], v[194:195] op_sel_hi:[1,0]
	v_pk_mul_f32 v[32:33], v[32:33], v[194:195] op_sel_hi:[1,0]
	v_exp_f32_e32 v41, v41
	v_pk_mul_f32 v[22:23], v[22:23], v[194:195] op_sel_hi:[1,0]
	v_pk_add_f32 v[40:41], v[40:41], v[140:141]
	v_rcp_f32_e32 v46, v46
	v_pk_mul_f32 v[24:25], v[24:25], v[194:195] op_sel_hi:[1,0]
	v_mul_f32_e32 v210, v144, v144
	v_rcp_f32_e32 v47, v47
	v_pk_mul_f32 v[26:27], v[26:27], v[210:211] op_sel_hi:[1,0]
	v_pk_mul_f32 v[42:43], v[42:43], v[46:47]
	v_rcp_f32_e32 v48, v48
	v_cvt_pk_bf16_f32 v46, v42, v43
	v_pk_mul_f32 v[28:29], v[28:29], v[210:211] op_sel_hi:[1,0]
	v_rcp_f32_e32 v49, v49
	v_pk_mul_f32 v[18:19], v[18:19], v[210:211] op_sel_hi:[1,0]
	v_pk_mul_f32 v[44:45], v[44:45], v[48:49]
	v_rcp_f32_e32 v38, v38
	v_cvt_pk_bf16_f32 v47, v44, v45
	v_pk_mul_f32 v[20:21], v[20:21], v[210:211] op_sel_hi:[1,0]
	v_rcp_f32_e32 v39, v39
	v_ffbh_u32_e32 v196, v143
	v_pk_mul_f32 v[34:35], v[34:35], v[38:39]
	v_rcp_f32_e32 v40, v40
	v_cvt_pk_bf16_f32 v48, v34, v35
	v_min_u32_e32 v196, 32, v196
	v_rcp_f32_e32 v41, v41
	v_lshlrev_b64 v[142:143], v196, v[142:143]
	v_pk_mul_f32 v[36:37], v[36:37], v[40:41]
	v_exp_f32_e32 v30, v30
	v_cvt_pk_bf16_f32 v49, v36, v37
	global_store_dwordx4 v[156:157], v[46:49], off
	v_exp_f32_e32 v31, v31
	v_lshl_add_u64 v[156:157], v[156:157], 0, s[4:5]
	v_pk_add_f32 v[30:31], v[30:31], v[140:141]
	v_exp_f32_e32 v32, v32
	v_min_u32_e32 v212, 1, v142
	v_or_b32_e32 v212, v143, v212
	v_exp_f32_e32 v33, v33
	v_cvt_f32_u32_e32 v212, v212
	v_pk_add_f32 v[32:33], v[32:33], v[140:141]
	v_exp_f32_e32 v22, v22
	v_sub_u32_e32 v196, 32, v196
	v_ldexp_f32 v212, v212, v196
	v_exp_f32_e32 v23, v23
	v_mul_f32_e32 v212, 0x33800000, v212
	v_pk_add_f32 v[22:23], v[22:23], v[140:141]
	v_exp_f32_e32 v24, v24
	v_fmamk_f32 v212, v212, 0x3a000000, v218
	v_exp_f32_e32 v25, v25
	v_rcp_f32_e32 v30, v30
	v_pk_add_f32 v[24:25], v[24:25], v[140:141]
	v_rcp_f32_e32 v31, v31
	v_rcp_f32_e32 v32, v32
	v_pk_mul_f32 v[26:27], v[26:27], v[30:31]
	v_rcp_f32_e32 v33, v33
	v_cvt_pk_bf16_f32 v30, v26, v27
	v_pk_mul_f32 v[28:29], v[28:29], v[32:33]
	v_rcp_f32_e32 v22, v22
	v_cvt_pk_bf16_f32 v31, v28, v29
	v_rcp_f32_e32 v23, v23
	v_rcp_f32_e32 v24, v24
	v_pk_mul_f32 v[18:19], v[18:19], v[22:23]
	v_rcp_f32_e32 v25, v25
	v_cvt_pk_bf16_f32 v32, v18, v19
	v_pk_mul_f32 v[20:21], v[20:21], v[24:25]
	v_rsq_f32_e32 v142, v212
	v_cvt_pk_bf16_f32 v33, v20, v21
	global_store_dwordx4 v[156:157], v[30:33], off
	v_mul_f32_e32 v196, 0xbfb8aa3b, v142
	v_pk_mul_f32 v[14:15], v[14:15], v[196:197] op_sel_hi:[1,0]
	v_pk_mul_f32 v[16:17], v[16:17], v[196:197] op_sel_hi:[1,0]
	v_exp_f32_e32 v14, v14
	v_pk_mul_f32 v[6:7], v[6:7], v[196:197] op_sel_hi:[1,0]
	v_pk_mul_f32 v[8:9], v[8:9], v[196:197] op_sel_hi:[1,0]
	v_exp_f32_e32 v15, v15
	v_mul_f32_e32 v212, v142, v142
	v_pk_add_f32 v[14:15], v[14:15], v[140:141]
	v_exp_f32_e32 v16, v16
	v_pk_mul_f32 v[10:11], v[10:11], v[212:213] op_sel_hi:[1,0]
	v_pk_mul_f32 v[12:13], v[12:13], v[212:213] op_sel_hi:[1,0]
	v_exp_f32_e32 v17, v17
	v_pk_mul_f32 v[2:3], v[2:3], v[212:213] op_sel_hi:[1,0]
	v_pk_add_f32 v[16:17], v[16:17], v[140:141]
	v_exp_f32_e32 v6, v6
	v_pk_mul_f32 v[4:5], v[4:5], v[212:213] op_sel_hi:[1,0]
	v_lshl_add_u64 v[156:157], v[156:157], 0, s[4:5]
	v_exp_f32_e32 v7, v7
	v_exp_f32_e32 v8, v8
	v_pk_add_f32 v[6:7], v[6:7], v[140:141]
	v_exp_f32_e32 v9, v9
	v_rcp_f32_e32 v14, v14
	v_pk_add_f32 v[8:9], v[8:9], v[140:141]
	v_rcp_f32_e32 v15, v15
	v_rcp_f32_e32 v16, v16
	v_pk_mul_f32 v[10:11], v[10:11], v[14:15]
	v_rcp_f32_e32 v17, v17
	v_cvt_pk_bf16_f32 v14, v10, v11
	v_pk_mul_f32 v[12:13], v[12:13], v[16:17]
	v_rcp_f32_e32 v6, v6
	v_cvt_pk_bf16_f32 v15, v12, v13
	v_rcp_f32_e32 v7, v7
	v_rcp_f32_e32 v8, v8
	v_pk_mul_f32 v[2:3], v[2:3], v[6:7]
	v_rcp_f32_e32 v9, v9
	v_cvt_pk_bf16_f32 v16, v2, v3
	v_pk_mul_f32 v[4:5], v[4:5], v[8:9]
	s_nop 0
	v_cvt_pk_bf16_f32 v17, v4, v5
	global_store_dwordx4 v[156:157], v[14:17], off
	s_mov_b64 s[4:5], -1
	s_andn2_b64 vcc, exec, s[8:9]
	s_cbranch_vccnz .LBB0_867
	s_andn2_b64 vcc, exec, s[10:11]
	s_cbranch_vccnz .LBB0_866
	s_barrier
	s_branch .LBB0_866
